# MIX item lists re-balanced statically: 128 item blocks take both halves-of-a-prompt-chain items, the other 256 take one diff-sample + one std-sample + the small prompt-attention / LRU items (was: a st
# speedup vs baseline: 1.0020x; 1.0020x over previous
.LBB0_1136:
	s_andn2_b64 vcc, exec, s[0:1]
	s_cbranch_vccnz .LBB0_1017
	v_readlane_b32 s2, v207, 49
	v_readlane_b32 s3, v207, 50
	s_mov_b64 s[0:1], -1
	s_and_b64 vcc, exec, s[2:3]
	s_cbranch_vccz .LBB0_1233
	v_readlane_b32 s0, v207, 52
	v_readlane_b32 s1, v207, 53
	s_andn2_b64 vcc, exec, s[0:1]
	v_readlane_b32 s51, v209, 0
	s_nop 3
	s_add_i32 s0, s51, 0x80
	s_sub_i32 s2, s51, 0x80
	s_cmpk_lt_u32 s51, 0x180
	s_cselect_b32 s0, s0, s2
	s_cmpk_lt_u32 s51, 0x100
	s_cselect_b32 s51, s51, s0
	s_add_i32 s0, s51, 0x80
	s_cmpk_lt_u32 s51, 0x100
	s_cselect_b32 s51, s51, s0
	s_mov_b32 s85, s51
	s_lshl_b32 s0, s51, 5
	v_writelane_b32 v206, s0, 51
	s_lshl_b32 s0, s51, 6
	s_add_i32 s0, s0, 0xffff5600
	v_writelane_b32 v205, s0, 31
	s_lshl_b32 s31, s51, 4
	s_addk_i32 s31, 0xc580
	s_add_i32 s30, s51, 0xfffffb58
	s_lshl_b32 s0, s51, 4
	s_add_i32 s0, s0, 0xffffb580
	v_writelane_b32 v205, s0, 29
	s_cbranch_vccz .LBB0_1152

.LBB0_1151:
	v_readlane_b32 s0, v209, 0
	s_nop 3
	s_add_i32 s1, s0, 0x80
	s_sub_i32 s2, s0, 0x80
	s_cmpk_lt_u32 s0, 0x180
	s_cselect_b32 s1, s1, s2
	s_cmpk_lt_u32 s0, 0x100
	s_cselect_b32 s0, s0, s1
	s_sub_i32 s1, s85, s0
	s_cmpk_lt_u32 s0, 0x100
	s_cbranch_scc0 .Lms_y
	s_movk_i32 s2, 128
	s_cmpk_eq_u32 s1, 0
	s_cbranch_scc1 .Lms_set
	s_branch .LBB0_1139
.Lms_y:
	s_movk_i32 s2, 424
	s_cmpk_eq_u32 s1, 128
	s_cbranch_scc1 .Lms_set
	s_movk_i32 s2, 680
	s_cmpk_eq_u32 s1, 424
	s_cbranch_scc1 .Lms_set
	s_movk_i32 s2, 936
	s_cmpk_eq_u32 s1, 680
	s_cbranch_scc1 .Lms_set
	s_cmpk_eq_u32 s1, 936
	s_cbranch_scc0 .LBB0_1139
	s_movk_i32 s2, 384
	s_cmpk_lt_u32 s0, 0x128
	s_cbranch_scc0 .LBB0_1139
.Lms_set:
	s_add_i32 s85, s0, s2
	s_lshl_b32 s0, s85, 5
	v_writelane_b32 v206, s0, 51
	s_lshl_b32 s0, s85, 6
	s_add_i32 s0, s0, 0xffff5600
	v_writelane_b32 v205, s0, 31
	s_lshl_b32 s31, s85, 4
	s_addk_i32 s31, 0xc580
	s_add_i32 s30, s85, 0xfffffb58
	s_lshl_b32 s0, s85, 4
	s_add_i32 s0, s0, 0xffffb580
	v_writelane_b32 v205, s0, 29
